# idle waves touch the first K-slab of the next GEMM phase's weights (up, down, w_in) during the grid barrier so the phase prologue finds them in L2/MALL
# speedup vs baseline: 1.0078x; 1.0078x over previous
; #define GSYNC() do { for (int _r = 0; _r < SYNC_REPS; ++_r) xcd_barrier(xbar); } while (0)
; __device__ __forceinline__ PP get_pp() { PP q = (PP)__builtin_amdgcn_kernarg_segment_ptr(); asm volatile("" : "+s"(q)); return q; }
; __device__ __forceinline__ void xcd_barrier(const XcdBarrier& b) {
;     asm volatile("s_waitcnt vmcnt(0)" ::: "memory");
;     __syncthreads();
;     if (threadIdx.x == 0) {
;         unsigned* bar = b.bar;
;         __builtin_amdgcn_s_waitcnt(0);
;         unsigned nloc = b.st[0], nx = b.st[1];
;         if (nloc == 0u) { xcd_barrier_complete(bar, b.x, nloc, nx); b.st[0] = nloc; b.st[1] = nx; }
; __global__ void __launch_bounds__(512, 2) hymba_fwd(Params p_unused) {
;     ...
;         GSYNC();
;         { PP p = get_pp(); unsigned char* ws = p->ws;
;           pg8::EpiBf16<1> E{(bf16_t*)(ws + WS_ACT), DFF, 1.0f, nullptr};
;           run_gemm(shm, (const bf16_t*)(ws + WS_XN), (const bf16_t*)(ws + WS_WUP) + (size_t)l * DFF * D, T, DFF, D, E); }
.Lxbi8_skip:
	s_cmp_lt_u32 s98, 2
	s_cbranch_scc1 .Lpf8_skip
	s_load_dwordx2 s[2:3], s[0:1], 0x110
	v_readlane_b32 s12, v255, 20
	v_readlane_b32 s13, v254, 2
	s_nop 3
	s_mul_i32 s12, s12, 0x2000000
	s_add_u32 s12, s12, 0x7800000
	s_mul_i32 s13, s13, 0x180
	v_add_u32_e32 v2, 0xffffff80, v222
	v_add_u32_e32 v2, s13, v2
	s_waitcnt lgkmcnt(0)
	s_add_u32 s2, s2, s12
	s_addc_u32 s3, s3, 0
	s_mov_b32 s99, 0x20000
	v_cmp_gt_u32_e32 vcc, s99, v2
	s_and_saveexec_b64 s[12:13], vcc
	v_lshrrev_b32_e32 v3, 4, v2
	v_and_b32_e32 v4, 15, v2
	v_lshlrev_b32_e32 v3, 12, v3
	v_lshl_add_u32 v3, v4, 4, v3
	s_nop 0
	global_load_dwordx4 v[10:13], v3, s[2:3] sc1
	s_or_b64 exec, exec, s[12:13]
	v_add_u32_e32 v2, 0x18000, v2
	v_cmp_gt_u32_e32 vcc, s99, v2
	s_and_saveexec_b64 s[12:13], vcc
	v_lshrrev_b32_e32 v3, 4, v2
	v_and_b32_e32 v4, 15, v2
	v_lshlrev_b32_e32 v3, 12, v3
	v_lshl_add_u32 v3, v4, 4, v3
	s_nop 0
	global_load_dwordx4 v[14:17], v3, s[2:3] sc1
	s_or_b64 exec, exec, s[12:13]
	v_add_u32_e32 v2, 0x18000, v2
.Lpf8_wait:
	s_waitcnt vmcnt(0) lgkmcnt(0)
.Lpf8_skip:
	s_mov_b64 s[8:9], exec
	v_readlane_b32 s2, v254, 0
	v_readlane_b32 s3, v254, 1
	s_and_b64 s[2:3], s[8:9], s[2:3]
	s_mov_b64 exec, s[2:3]
	s_cbranch_execz .LBB0_1327
	v_readlane_b32 s2, v254, 59
	s_waitcnt vmcnt(0) expcnt(0) lgkmcnt(0)
	s_nop 0
	v_mov_b32_e32 v0, s2
	ds_read_b32 v3, v0
	v_readlane_b32 s2, v254, 60
	s_waitcnt lgkmcnt(0)
	v_cmp_ne_u32_e32 vcc, 0, v3
	v_mov_b32_e32 v0, s2
	ds_read_b32 v2, v0
	s_cbranch_vccnz .LBB0_1291
	s_mov_b32 s14, 1
	s_branch .LBB0_1279

; #define GSYNC() do { for (int _r = 0; _r < SYNC_REPS; ++_r) xcd_barrier(xbar); } while (0)
; __device__ __forceinline__ PP get_pp() { PP q = (PP)__builtin_amdgcn_kernarg_segment_ptr(); asm volatile("" : "+s"(q)); return q; }
; __device__ __forceinline__ void xcd_barrier(const XcdBarrier& b) {
;     asm volatile("s_waitcnt vmcnt(0)" ::: "memory");
;     __syncthreads();
;     if (threadIdx.x == 0) {
;         unsigned* bar = b.bar;
;         __builtin_amdgcn_s_waitcnt(0);
;         unsigned nloc = b.st[0], nx = b.st[1];
;         if (nloc == 0u) { xcd_barrier_complete(bar, b.x, nloc, nx); b.st[0] = nloc; b.st[1] = nx; }
; __global__ void __launch_bounds__(512, 2) hymba_fwd(Params p_unused) {
;     ...
;         GSYNC();
;         { PP p = get_pp(); unsigned char* ws = p->ws;
;           pg8::EpiRes2<2, false> E{nullptr, (bf16_t*)(ws + WS_XN), (unsigned char*)(ws + WS_H), (float*)(ws + WS_SS) + (size_t)(3 + 3 * l) * T * 32, (const float*)(ws + WS_SS) + (size_t)(2 + 3 * l) * T * 32};
;           run_gemm(shm, (const bf16_t*)(ws + WS_ACT), (const bf16_t*)(ws + WS_WDN) + (size_t)l * D * DFF, T, D, DFF, E); }
.Lxbi9_skip:
	s_cmp_lt_u32 s98, 2
	s_cbranch_scc1 .Lpf9_skip
	s_load_dwordx2 s[2:3], s[0:1], 0x110
	v_readlane_b32 s12, v255, 20
	v_readlane_b32 s13, v254, 2
	s_nop 3
	s_mul_i32 s12, s12, 0x2000000
	s_add_u32 s12, s12, 0xf800000
	s_mul_i32 s13, s13, 0x180
	v_add_u32_e32 v2, 0xffffff80, v222
	v_add_u32_e32 v2, s13, v2
	s_waitcnt lgkmcnt(0)
	s_add_u32 s2, s2, s12
	s_addc_u32 s3, s3, 0
	s_mov_b32 s99, 0x8000
	v_cmp_gt_u32_e32 vcc, s99, v2
	s_and_saveexec_b64 s[12:13], vcc
	v_lshrrev_b32_e32 v3, 4, v2
	v_and_b32_e32 v4, 15, v2
	v_lshlrev_b32_e32 v3, 14, v3
	v_lshl_add_u32 v3, v4, 4, v3
	s_nop 0
	global_load_dwordx4 v[10:13], v3, s[2:3] sc1
	s_or_b64 exec, exec, s[12:13]
	v_add_u32_e32 v2, 0x18000, v2
.Lpf9_wait:
	s_waitcnt vmcnt(0) lgkmcnt(0)
.Lpf9_skip:
	s_mov_b64 s[8:9], exec
	v_readlane_b32 s2, v254, 0
	v_readlane_b32 s3, v254, 1
	s_and_b64 s[2:3], s[8:9], s[2:3]
	s_mov_b64 exec, s[2:3]
	s_cbranch_execz .LBB0_1403
	v_readlane_b32 s2, v254, 59
	s_waitcnt vmcnt(0) expcnt(0) lgkmcnt(0)
	s_nop 0
	v_mov_b32_e32 v0, s2
	ds_read_b32 v3, v0
	v_readlane_b32 s2, v254, 60
	s_waitcnt lgkmcnt(0)
	v_cmp_ne_u32_e32 vcc, 0, v3
	v_mov_b32_e32 v0, s2
	ds_read_b32 v2, v0
	s_cbranch_vccnz .LBB0_1367
	s_mov_b32 s14, 1
	s_branch .LBB0_1355

; #define GSYNC() do { for (int _r = 0; _r < SYNC_REPS; ++_r) xcd_barrier(xbar); } while (0)
; __device__ __forceinline__ void xcd_barrier(const XcdBarrier& b) {
;     asm volatile("s_waitcnt vmcnt(0)" ::: "memory");
;     __syncthreads();
;     if (threadIdx.x == 0) {
;         unsigned* bar = b.bar;
;         __builtin_amdgcn_s_waitcnt(0);
;         unsigned nloc = b.st[0], nx = b.st[1];
;         if (nloc == 0u) { xcd_barrier_complete(bar, b.x, nloc, nx); b.st[0] = nloc; b.st[1] = nx; }
; __global__ void __launch_bounds__(512, 2) hymba_fwd(Params p_unused) {
;     ...
;         GSYNC();
;     }
.Lxbi10_skip:
	s_cmp_lt_u32 s98, 2
	s_cbranch_scc1 .Lpf10_skip
	s_load_dwordx2 s[2:3], s[0:1], 0x110
	v_readlane_b32 s12, v255, 20
	v_readlane_b32 s13, v254, 2
	s_nop 3
	s_add_i32 s12, s12, 1
	s_cmp_lt_u32 s12, 4
	s_cbranch_scc0 .Lpf10_wait
	s_mul_i32 s12, s12, 0xe00000
	s_add_u32 s12, s12, 0x0
	s_mul_i32 s13, s13, 0x180
	v_add_u32_e32 v2, 0xffffff80, v222
	v_add_u32_e32 v2, s13, v2
	s_waitcnt lgkmcnt(0)
	s_add_u32 s2, s2, s12
	s_addc_u32 s3, s3, 0
	s_mov_b32 s99, 0xe000
	v_cmp_gt_u32_e32 vcc, s99, v2
	s_and_saveexec_b64 s[12:13], vcc
	v_lshrrev_b32_e32 v3, 4, v2
	v_and_b32_e32 v4, 15, v2
	v_lshlrev_b32_e32 v3, 12, v3
	v_lshl_add_u32 v3, v4, 4, v3
	s_nop 0
	global_load_dwordx4 v[10:13], v3, s[2:3] sc1
	s_or_b64 exec, exec, s[12:13]
	v_add_u32_e32 v2, 0x18000, v2
.Lpf10_wait:
	s_waitcnt vmcnt(0) lgkmcnt(0)
.Lpf10_skip:
	s_mov_b64 s[8:9], exec
	v_readlane_b32 s2, v254, 0
	v_readlane_b32 s3, v254, 1
	s_and_b64 s[2:3], s[8:9], s[2:3]
	v_readlane_b32 s14, v255, 17
	s_mov_b64 exec, s[2:3]
	s_cbranch_execnz .LBB0_1446
	s_getpc_b64 s[98:99]
